# loop-edge edits: PREP dispatcher tests the heaviest quarter first without the padding nops; solve output address arithmetic replaces the s_nop cover of the MFMA result latency
# speedup vs baseline: 1.0117x; 1.0117x over previous
.Lsx0_d:
	s_setprio 3
	v_lshrrev_b32_e32 v96, 6, v198
	v_mul_u32_u24_e32 v96, 0x500, v96
	v_mad_u32_u24 v96, v145, 20, v96
	v_and_b32_e32 v97, 15, v198
	v_lshl_add_u32 v96, v97, 1, v96
	v_add_u32_e32 v96, 0x10a00, v96
	s_waitcnt lgkmcnt(0)
	s_nop 1
	v_fmac_f32_dpp v30, v30, v80 row_newbcast:0 row_mask:0xf bank_mask:0xf
	v_fmac_f32_dpp v31, v31, v80 row_newbcast:0 row_mask:0xf bank_mask:0xf
	v_fmac_f32_dpp v32, v32, v80 row_newbcast:0 row_mask:0xf bank_mask:0xf
	v_fmac_f32_dpp v33, v33, v80 row_newbcast:0 row_mask:0xf bank_mask:0xf
	v_fmac_f32_dpp v30, v30, v81 row_newbcast:1 row_mask:0xf bank_mask:0xf
	v_fmac_f32_dpp v31, v31, v81 row_newbcast:1 row_mask:0xf bank_mask:0xf
	v_fmac_f32_dpp v32, v32, v81 row_newbcast:1 row_mask:0xf bank_mask:0xf
	v_fmac_f32_dpp v33, v33, v81 row_newbcast:1 row_mask:0xf bank_mask:0xf
	v_fmac_f32_dpp v30, v30, v82 row_newbcast:2 row_mask:0xf bank_mask:0xf
	v_fmac_f32_dpp v31, v31, v82 row_newbcast:2 row_mask:0xf bank_mask:0xf
	v_fmac_f32_dpp v32, v32, v82 row_newbcast:2 row_mask:0xf bank_mask:0xf
	v_fmac_f32_dpp v33, v33, v82 row_newbcast:2 row_mask:0xf bank_mask:0xf
	v_fmac_f32_dpp v30, v30, v83 row_newbcast:3 row_mask:0xf bank_mask:0xf
	v_fmac_f32_dpp v31, v31, v83 row_newbcast:3 row_mask:0xf bank_mask:0xf
	v_fmac_f32_dpp v32, v32, v83 row_newbcast:3 row_mask:0xf bank_mask:0xf
	v_fmac_f32_dpp v33, v33, v83 row_newbcast:3 row_mask:0xf bank_mask:0xf
	v_fmac_f32_dpp v30, v30, v84 row_newbcast:4 row_mask:0xf bank_mask:0xf
	v_fmac_f32_dpp v31, v31, v84 row_newbcast:4 row_mask:0xf bank_mask:0xf
	v_fmac_f32_dpp v32, v32, v84 row_newbcast:4 row_mask:0xf bank_mask:0xf
	v_fmac_f32_dpp v33, v33, v84 row_newbcast:4 row_mask:0xf bank_mask:0xf
	v_fmac_f32_dpp v30, v30, v85 row_newbcast:5 row_mask:0xf bank_mask:0xf
	v_fmac_f32_dpp v31, v31, v85 row_newbcast:5 row_mask:0xf bank_mask:0xf
	v_fmac_f32_dpp v32, v32, v85 row_newbcast:5 row_mask:0xf bank_mask:0xf
	v_fmac_f32_dpp v33, v33, v85 row_newbcast:5 row_mask:0xf bank_mask:0xf
	v_fmac_f32_dpp v30, v30, v86 row_newbcast:6 row_mask:0xf bank_mask:0xf
	v_fmac_f32_dpp v31, v31, v86 row_newbcast:6 row_mask:0xf bank_mask:0xf
	v_fmac_f32_dpp v32, v32, v86 row_newbcast:6 row_mask:0xf bank_mask:0xf
	v_fmac_f32_dpp v33, v33, v86 row_newbcast:6 row_mask:0xf bank_mask:0xf
	v_fmac_f32_dpp v30, v30, v87 row_newbcast:7 row_mask:0xf bank_mask:0xf
	v_fmac_f32_dpp v31, v31, v87 row_newbcast:7 row_mask:0xf bank_mask:0xf
	v_fmac_f32_dpp v32, v32, v87 row_newbcast:7 row_mask:0xf bank_mask:0xf
	v_fmac_f32_dpp v33, v33, v87 row_newbcast:7 row_mask:0xf bank_mask:0xf
	v_fmac_f32_dpp v30, v30, v88 row_newbcast:8 row_mask:0xf bank_mask:0xf
	v_fmac_f32_dpp v31, v31, v88 row_newbcast:8 row_mask:0xf bank_mask:0xf
	v_fmac_f32_dpp v32, v32, v88 row_newbcast:8 row_mask:0xf bank_mask:0xf
	v_fmac_f32_dpp v33, v33, v88 row_newbcast:8 row_mask:0xf bank_mask:0xf
	v_fmac_f32_dpp v30, v30, v89 row_newbcast:9 row_mask:0xf bank_mask:0xf
	v_fmac_f32_dpp v31, v31, v89 row_newbcast:9 row_mask:0xf bank_mask:0xf
	v_fmac_f32_dpp v32, v32, v89 row_newbcast:9 row_mask:0xf bank_mask:0xf
	v_fmac_f32_dpp v33, v33, v89 row_newbcast:9 row_mask:0xf bank_mask:0xf
	v_fmac_f32_dpp v30, v30, v90 row_newbcast:10 row_mask:0xf bank_mask:0xf
	v_fmac_f32_dpp v31, v31, v90 row_newbcast:10 row_mask:0xf bank_mask:0xf
	v_fmac_f32_dpp v32, v32, v90 row_newbcast:10 row_mask:0xf bank_mask:0xf
	v_fmac_f32_dpp v33, v33, v90 row_newbcast:10 row_mask:0xf bank_mask:0xf
	v_fmac_f32_dpp v30, v30, v91 row_newbcast:11 row_mask:0xf bank_mask:0xf
	v_fmac_f32_dpp v31, v31, v91 row_newbcast:11 row_mask:0xf bank_mask:0xf
	v_fmac_f32_dpp v32, v32, v91 row_newbcast:11 row_mask:0xf bank_mask:0xf
	v_fmac_f32_dpp v33, v33, v91 row_newbcast:11 row_mask:0xf bank_mask:0xf
	v_fmac_f32_dpp v30, v30, v92 row_newbcast:12 row_mask:0xf bank_mask:0xf
	v_fmac_f32_dpp v31, v31, v92 row_newbcast:12 row_mask:0xf bank_mask:0xf
	v_fmac_f32_dpp v32, v32, v92 row_newbcast:12 row_mask:0xf bank_mask:0xf
	v_fmac_f32_dpp v33, v33, v92 row_newbcast:12 row_mask:0xf bank_mask:0xf
	v_fmac_f32_dpp v30, v30, v93 row_newbcast:13 row_mask:0xf bank_mask:0xf
	v_fmac_f32_dpp v31, v31, v93 row_newbcast:13 row_mask:0xf bank_mask:0xf
	v_fmac_f32_dpp v32, v32, v93 row_newbcast:13 row_mask:0xf bank_mask:0xf
	v_fmac_f32_dpp v33, v33, v93 row_newbcast:13 row_mask:0xf bank_mask:0xf
	v_fmac_f32_dpp v30, v30, v94 row_newbcast:14 row_mask:0xf bank_mask:0xf
	v_fmac_f32_dpp v31, v31, v94 row_newbcast:14 row_mask:0xf bank_mask:0xf
	v_fmac_f32_dpp v32, v32, v94 row_newbcast:14 row_mask:0xf bank_mask:0xf
	v_fmac_f32_dpp v33, v33, v94 row_newbcast:14 row_mask:0xf bank_mask:0xf
	v_cvt_pk_bf16_f32 v80, v30, v31
	v_cvt_pk_bf16_f32 v81, v32, v33
	ds_write_b16 v96, v80 offset:0
	ds_write_b16_d16_hi v96, v80 offset:80
	ds_write_b16 v96, v81 offset:160
	ds_write_b16_d16_hi v96, v81 offset:240
	s_setprio 1

.LBB0_405:
	v_lshrrev_b32_e32 v122, 6, v198
	s_nop 0
	v_readfirstlane_b32 s98, v122
	s_cmp_eq_u32 s98, 3
	s_cbranch_scc1 .Lpq0_q3
	s_cmp_eq_u32 s98, 2
	s_cbranch_scc1 .Lpq0_q2
	s_cmp_eq_u32 s98, 1
	s_cbranch_scc1 .Lpq0_q1
	s_cmp_eq_u32 s98, 0
	s_cbranch_scc1 .Lpq0_q0
	s_branch .Lpq0_end

.Lis1b:
	v_cvt_pk_bf16_f32 v240, v236, v237
	global_store_dword v[238:239], v240, off
	s_setprio 3
	v_lshrrev_b32_e32 v96, 6, v198
	v_mul_u32_u24_e32 v96, 0x500, v96
	v_mad_u32_u24 v96, v145, 20, v96
	v_and_b32_e32 v97, 15, v198
	v_lshl_add_u32 v96, v97, 1, v96
	v_add_u32_e32 v96, 0x10a00, v96
	s_waitcnt lgkmcnt(0)
	s_nop 1
	v_fmac_f32_dpp v30, v30, v80 row_newbcast:0 row_mask:0xf bank_mask:0xf
	v_fmac_f32_dpp v31, v31, v80 row_newbcast:0 row_mask:0xf bank_mask:0xf
	v_fmac_f32_dpp v32, v32, v80 row_newbcast:0 row_mask:0xf bank_mask:0xf
	v_fmac_f32_dpp v33, v33, v80 row_newbcast:0 row_mask:0xf bank_mask:0xf
	v_fmac_f32_dpp v30, v30, v81 row_newbcast:1 row_mask:0xf bank_mask:0xf
	v_fmac_f32_dpp v31, v31, v81 row_newbcast:1 row_mask:0xf bank_mask:0xf
	v_fmac_f32_dpp v32, v32, v81 row_newbcast:1 row_mask:0xf bank_mask:0xf
	v_fmac_f32_dpp v33, v33, v81 row_newbcast:1 row_mask:0xf bank_mask:0xf
	v_fmac_f32_dpp v30, v30, v82 row_newbcast:2 row_mask:0xf bank_mask:0xf
	v_fmac_f32_dpp v31, v31, v82 row_newbcast:2 row_mask:0xf bank_mask:0xf
	v_fmac_f32_dpp v32, v32, v82 row_newbcast:2 row_mask:0xf bank_mask:0xf
	v_fmac_f32_dpp v33, v33, v82 row_newbcast:2 row_mask:0xf bank_mask:0xf
	v_fmac_f32_dpp v30, v30, v83 row_newbcast:3 row_mask:0xf bank_mask:0xf
	v_fmac_f32_dpp v31, v31, v83 row_newbcast:3 row_mask:0xf bank_mask:0xf
	v_fmac_f32_dpp v32, v32, v83 row_newbcast:3 row_mask:0xf bank_mask:0xf
	v_fmac_f32_dpp v33, v33, v83 row_newbcast:3 row_mask:0xf bank_mask:0xf
	v_fmac_f32_dpp v30, v30, v84 row_newbcast:4 row_mask:0xf bank_mask:0xf
	v_fmac_f32_dpp v31, v31, v84 row_newbcast:4 row_mask:0xf bank_mask:0xf
	v_fmac_f32_dpp v32, v32, v84 row_newbcast:4 row_mask:0xf bank_mask:0xf
	v_fmac_f32_dpp v33, v33, v84 row_newbcast:4 row_mask:0xf bank_mask:0xf
	v_fmac_f32_dpp v30, v30, v85 row_newbcast:5 row_mask:0xf bank_mask:0xf
	v_fmac_f32_dpp v31, v31, v85 row_newbcast:5 row_mask:0xf bank_mask:0xf
	v_fmac_f32_dpp v32, v32, v85 row_newbcast:5 row_mask:0xf bank_mask:0xf
	v_fmac_f32_dpp v33, v33, v85 row_newbcast:5 row_mask:0xf bank_mask:0xf
	v_fmac_f32_dpp v30, v30, v86 row_newbcast:6 row_mask:0xf bank_mask:0xf
	v_fmac_f32_dpp v31, v31, v86 row_newbcast:6 row_mask:0xf bank_mask:0xf
	v_fmac_f32_dpp v32, v32, v86 row_newbcast:6 row_mask:0xf bank_mask:0xf
	v_fmac_f32_dpp v33, v33, v86 row_newbcast:6 row_mask:0xf bank_mask:0xf
	v_fmac_f32_dpp v30, v30, v87 row_newbcast:7 row_mask:0xf bank_mask:0xf
	v_fmac_f32_dpp v31, v31, v87 row_newbcast:7 row_mask:0xf bank_mask:0xf
	v_fmac_f32_dpp v32, v32, v87 row_newbcast:7 row_mask:0xf bank_mask:0xf
	v_fmac_f32_dpp v33, v33, v87 row_newbcast:7 row_mask:0xf bank_mask:0xf
	v_fmac_f32_dpp v30, v30, v88 row_newbcast:8 row_mask:0xf bank_mask:0xf
	v_fmac_f32_dpp v31, v31, v88 row_newbcast:8 row_mask:0xf bank_mask:0xf
	v_fmac_f32_dpp v32, v32, v88 row_newbcast:8 row_mask:0xf bank_mask:0xf
	v_fmac_f32_dpp v33, v33, v88 row_newbcast:8 row_mask:0xf bank_mask:0xf
	v_fmac_f32_dpp v30, v30, v89 row_newbcast:9 row_mask:0xf bank_mask:0xf
	v_fmac_f32_dpp v31, v31, v89 row_newbcast:9 row_mask:0xf bank_mask:0xf
	v_fmac_f32_dpp v32, v32, v89 row_newbcast:9 row_mask:0xf bank_mask:0xf
	v_fmac_f32_dpp v33, v33, v89 row_newbcast:9 row_mask:0xf bank_mask:0xf
	v_fmac_f32_dpp v30, v30, v90 row_newbcast:10 row_mask:0xf bank_mask:0xf
	v_fmac_f32_dpp v31, v31, v90 row_newbcast:10 row_mask:0xf bank_mask:0xf
	v_fmac_f32_dpp v32, v32, v90 row_newbcast:10 row_mask:0xf bank_mask:0xf
	v_fmac_f32_dpp v33, v33, v90 row_newbcast:10 row_mask:0xf bank_mask:0xf
	v_fmac_f32_dpp v30, v30, v91 row_newbcast:11 row_mask:0xf bank_mask:0xf
	v_fmac_f32_dpp v31, v31, v91 row_newbcast:11 row_mask:0xf bank_mask:0xf
	v_fmac_f32_dpp v32, v32, v91 row_newbcast:11 row_mask:0xf bank_mask:0xf
	v_fmac_f32_dpp v33, v33, v91 row_newbcast:11 row_mask:0xf bank_mask:0xf
	v_fmac_f32_dpp v30, v30, v92 row_newbcast:12 row_mask:0xf bank_mask:0xf
	v_fmac_f32_dpp v31, v31, v92 row_newbcast:12 row_mask:0xf bank_mask:0xf
	v_fmac_f32_dpp v32, v32, v92 row_newbcast:12 row_mask:0xf bank_mask:0xf
	v_fmac_f32_dpp v33, v33, v92 row_newbcast:12 row_mask:0xf bank_mask:0xf
	v_fmac_f32_dpp v30, v30, v93 row_newbcast:13 row_mask:0xf bank_mask:0xf
	v_fmac_f32_dpp v31, v31, v93 row_newbcast:13 row_mask:0xf bank_mask:0xf
	v_fmac_f32_dpp v32, v32, v93 row_newbcast:13 row_mask:0xf bank_mask:0xf
	v_fmac_f32_dpp v33, v33, v93 row_newbcast:13 row_mask:0xf bank_mask:0xf
	v_fmac_f32_dpp v30, v30, v94 row_newbcast:14 row_mask:0xf bank_mask:0xf
	v_fmac_f32_dpp v31, v31, v94 row_newbcast:14 row_mask:0xf bank_mask:0xf
	v_fmac_f32_dpp v32, v32, v94 row_newbcast:14 row_mask:0xf bank_mask:0xf
	v_fmac_f32_dpp v33, v33, v94 row_newbcast:14 row_mask:0xf bank_mask:0xf
	v_cvt_pk_bf16_f32 v80, v30, v31
	v_cvt_pk_bf16_f32 v81, v32, v33
	ds_write_b16 v96, v80 offset:5120
	ds_write_b16_d16_hi v96, v80 offset:5200
	ds_write_b16 v96, v81 offset:5280
	ds_write_b16_d16_hi v96, v81 offset:5360
	s_setprio 1

.LBB0_434:
	v_lshrrev_b32_e32 v122, 6, v198
	s_nop 0
	v_readfirstlane_b32 s98, v122
	s_cmpk_lt_u32 s20, 0x7f
	s_cbranch_scc0 .Lpq1_end
	s_cmp_eq_u32 s98, 3
	s_cbranch_scc1 .Lpq1_q3
	s_cmp_eq_u32 s98, 2
	s_cbranch_scc1 .Lpq1_q2
	s_cmp_eq_u32 s98, 1
	s_cbranch_scc1 .Lpq1_q1
	s_cmp_eq_u32 s98, 0
	s_cbranch_scc1 .Lpq1_q0
	s_branch .Lpq1_end
